# grid barrier: the acquire invalidate is issued together with the arrival atomic (overlapped) instead of after it
# speedup vs baseline: 1.0133x; 1.0133x over previous
.LBB0_120:
	s_mov_b64 s[8:9], exec
	v_readlane_b32 s2, v252, 4
	s_lshl_b32 s2, s2, 8
	v_readlane_b32 s6, v252, 2
	v_mbcnt_lo_u32_b32 v1, s8, 0
	v_readlane_b32 s7, v252, 3
	s_add_u32 s6, s6, s2
	v_mbcnt_hi_u32_b32 v1, s9, v1
	s_addc_u32 s7, s7, 0
	v_cmp_eq_u32_e32 vcc, 0, v1
	s_and_saveexec_b64 s[10:11], vcc
	s_cbranch_execz .LBB0_122
	s_bcnt1_i32_b64 s2, s[8:9]
	v_mov_b32_e32 v3, 0x1000
	v_mov_b32_e32 v4, s2
	buffer_inv sc1
	global_atomic_add v3, v3, v4, s[6:7] offset:1024 sc0
